# conv pre-pass load balance: second-round wave tasks go to waves 0..3 of every CU instead of all waves of CUs 0..127
# speedup vs baseline: 1.0012x; 1.0012x over previous
.LBB0_329:
	v_lshl_add_u64 v[40:41], s[8:9], 0, v[78:79]
	v_add_co_u32_e32 v42, vcc, s11, v40
	s_waitcnt vmcnt(0)
	v_pk_fma_f32 v[60:61], v[4:5], v[60:61], v[36:37]
	v_addc_co_u32_e32 v43, vcc, 0, v41, vcc
	global_load_dwordx4 v[52:55], v[42:43], off offset:3072
	v_add_co_u32_e32 v42, vcc, s12, v40
	v_pk_fma_f32 v[60:61], v[8:9], v[66:67], v[60:61]
	s_nop 0
	v_addc_co_u32_e32 v43, vcc, 0, v41, vcc
	global_load_dwordx4 v[48:51], v[42:43], off offset:512
	v_add_co_u32_e32 v42, vcc, s13, v40
	v_mov_b32_e32 v68, v85
	s_nop 0
	v_addc_co_u32_e32 v43, vcc, 0, v41, vcc
	global_load_dwordx4 v[44:47], v[42:43], off offset:2048
	v_pk_fma_f32 v[60:61], v[16:17], v[68:69], v[60:61]
	v_add_co_u32_e32 v40, vcc, s14, v40
	v_pk_fma_f32 v[66:67], v[4:5], v[66:67], v[36:37]
	s_nop 0
	v_addc_co_u32_e32 v41, vcc, 0, v41, vcc
	global_load_dwordx4 v[40:43], v[40:41], off offset:3584
	v_pk_fma_f32 v[66:67], v[8:9], v[68:69], v[66:67]
	v_pk_fma_f32 v[68:69], v[4:5], v[68:69], v[36:37]
	v_pk_fma_f32 v[58:59], v[6:7], v[58:59], v[38:39]
	v_pk_fma_f32 v[62:63], v[2:3], v[62:63], v[34:35]
	v_pk_fma_f32 v[58:59], v[10:11], v[64:65], v[58:59]
	v_pk_fma_f32 v[64:65], v[6:7], v[64:65], v[38:39]
	v_pk_fma_f32 v[58:59], v[18:19], v[76:77], v[58:59]
	v_pk_fma_f32 v[64:65], v[10:11], v[76:77], v[64:65]
	v_pk_fma_f32 v[76:77], v[6:7], v[76:77], v[38:39]
	v_pk_fma_f32 v[62:63], v[14:15], v[70:71], v[62:63]
	v_lshl_add_u64 v[90:91], s[6:7], 0, v[78:79]
	v_pk_fma_f32 v[62:63], v[22:23], v[74:75], v[62:63]
	s_add_i32 s30, s30, 4
	s_add_u32 s6, s6, 0x6000
	s_addc_u32 s7, s7, 0
	s_add_u32 s8, s8, 0xd800
	s_addc_u32 s9, s9, 0
	s_cmp_gt_u32 s30, 11
	s_waitcnt vmcnt(3)
	v_lshlrev_b32_e32 v92, 16, v52
	v_and_b32_e32 v93, 0xffff0000, v52
	v_pk_fma_f32 v[60:61], v[24:25], v[92:93], v[60:61]
	v_pk_fma_f32 v[66:67], v[16:17], v[92:93], v[66:67]
	v_mul_f32_e32 v52, 0xbfb8aa3b, v60
	v_exp_f32_e32 v88, v52
	v_mul_f32_e32 v52, 0xbfb8aa3b, v61
	v_exp_f32_e32 v89, v52
	v_pk_fma_f32 v[68:69], v[8:9], v[92:93], v[68:69]
	v_pk_fma_f32 v[92:93], v[4:5], v[92:93], v[36:37]
	s_waitcnt vmcnt(2)
	v_and_b32_e32 v87, 0xffff0000, v50
	v_pk_add_f32 v[88:89], v[88:89], 1.0 op_sel_hi:[1,0]
	s_nop 0
	v_div_scale_f32 v52, s[34:35], v89, v89, v61
	v_rcp_f32_e32 v73, v52
	s_nop 0
	v_fma_f32 v85, -v52, v73, 1.0
	v_fmac_f32_e32 v73, v85, v73
	v_div_scale_f32 v85, vcc, v61, v89, v61
	v_mul_f32_e32 v86, v85, v73
	v_fma_f32 v94, -v52, v86, v85
	v_fmac_f32_e32 v86, v94, v73
	v_fma_f32 v52, -v52, v86, v85
	v_div_fmas_f32 v52, v52, v73, v86
	v_div_fixup_f32 v52, v52, v89, v61
	v_div_scale_f32 v61, s[34:35], v88, v88, v60
	v_rcp_f32_e32 v73, v61
	s_nop 0
	v_fma_f32 v85, -v61, v73, 1.0
	v_fmac_f32_e32 v73, v85, v73
	v_div_scale_f32 v85, vcc, v60, v88, v60
	v_mul_f32_e32 v86, v85, v73
	v_fma_f32 v89, -v61, v86, v85
	v_fmac_f32_e32 v86, v89, v73
	v_fma_f32 v61, -v61, v86, v85
	v_div_fmas_f32 v61, v61, v73, v86
	v_div_fixup_f32 v60, v61, v88, v60
	v_cvt_pk_bf16_f32 v52, v60, v52
	v_lshlrev_b32_e32 v60, 16, v48
	v_and_b32_e32 v61, 0xffff0000, v48
	v_pk_fma_f32 v[66:67], v[24:25], v[60:61], v[66:67]
	v_pk_fma_f32 v[68:69], v[16:17], v[60:61], v[68:69]
	v_mul_f32_e32 v48, 0xbfb8aa3b, v66
	v_exp_f32_e32 v88, v48
	v_mul_f32_e32 v48, 0xbfb8aa3b, v67
	v_exp_f32_e32 v89, v48
	v_pk_fma_f32 v[92:93], v[8:9], v[60:61], v[92:93]
	v_pk_add_f32 v[88:89], v[88:89], 1.0 op_sel_hi:[1,0]
	s_nop 0
	v_div_scale_f32 v48, s[34:35], v89, v89, v67
	v_rcp_f32_e32 v73, v48
	s_nop 0
	v_fma_f32 v85, -v48, v73, 1.0
	v_fmac_f32_e32 v73, v85, v73
	v_div_scale_f32 v85, vcc, v67, v89, v67
	v_mul_f32_e32 v86, v85, v73
	v_fma_f32 v94, -v48, v86, v85
	v_fmac_f32_e32 v86, v94, v73
	v_fma_f32 v48, -v48, v86, v85
	v_div_fmas_f32 v48, v48, v73, v86
	v_div_fixup_f32 v48, v48, v89, v67
	v_div_scale_f32 v67, s[34:35], v88, v88, v66
	v_rcp_f32_e32 v73, v67
	s_nop 0
	v_fma_f32 v85, -v67, v73, 1.0
	v_fmac_f32_e32 v73, v85, v73
	v_div_scale_f32 v85, vcc, v66, v88, v66
	v_mul_f32_e32 v86, v85, v73
	v_fma_f32 v89, -v67, v86, v85
	v_fmac_f32_e32 v86, v89, v73
	v_fma_f32 v67, -v67, v86, v85
	v_div_fmas_f32 v67, v67, v73, v86
	v_div_fixup_f32 v66, v67, v88, v66
	v_cvt_pk_bf16_f32 v48, v66, v48
	s_waitcnt vmcnt(1)
	v_lshlrev_b32_e32 v66, 16, v44
	v_and_b32_e32 v67, 0xffff0000, v44
	v_pk_fma_f32 v[68:69], v[24:25], v[66:67], v[68:69]
	v_pk_fma_f32 v[92:93], v[16:17], v[66:67], v[92:93]
	v_mul_f32_e32 v44, 0xbfb8aa3b, v68
	v_exp_f32_e32 v88, v44
	v_mul_f32_e32 v44, 0xbfb8aa3b, v69
	v_exp_f32_e32 v89, v44
	s_nop 0
	v_pk_add_f32 v[88:89], v[88:89], 1.0 op_sel_hi:[1,0]
	s_nop 0
	v_div_scale_f32 v44, s[34:35], v89, v89, v69
	v_rcp_f32_e32 v73, v44
	s_nop 0
	v_fma_f32 v85, -v44, v73, 1.0
	v_fmac_f32_e32 v73, v85, v73
	v_div_scale_f32 v85, vcc, v69, v89, v69
	v_mul_f32_e32 v86, v85, v73
	v_fma_f32 v94, -v44, v86, v85
	v_fmac_f32_e32 v86, v94, v73
	v_fma_f32 v44, -v44, v86, v85
	v_div_fmas_f32 v44, v44, v73, v86
	v_div_fixup_f32 v44, v44, v89, v69
	v_div_scale_f32 v69, s[34:35], v88, v88, v68
	v_rcp_f32_e32 v73, v69
	s_nop 0
	v_fma_f32 v85, -v69, v73, 1.0
	v_fmac_f32_e32 v73, v85, v73
	v_div_scale_f32 v85, vcc, v68, v88, v68
	v_mul_f32_e32 v86, v85, v73
	v_fma_f32 v89, -v69, v86, v85
	v_fmac_f32_e32 v86, v89, v73
	v_fma_f32 v69, -v69, v86, v85
	v_div_fmas_f32 v69, v69, v73, v86
	v_div_fixup_f32 v68, v69, v88, v68
	s_waitcnt vmcnt(0)
	v_lshlrev_b32_e32 v89, 16, v40
	v_cvt_pk_bf16_f32 v44, v68, v44
	v_and_b32_e32 v69, 0xffff0000, v40
	v_mov_b32_e32 v68, v89
	v_pk_fma_f32 v[92:93], v[24:25], v[68:69], v[92:93]
	v_lshlrev_b32_e32 v88, 16, v50
	v_mul_f32_e32 v40, 0xbfb8aa3b, v92
	v_exp_f32_e32 v94, v40
	v_mul_f32_e32 v40, 0xbfb8aa3b, v93
	v_exp_f32_e32 v95, v40
	s_nop 0
	v_pk_add_f32 v[94:95], v[94:95], 1.0 op_sel_hi:[1,0]
	s_nop 0
	v_div_scale_f32 v40, s[34:35], v95, v95, v93
	v_rcp_f32_e32 v50, v40
	s_nop 0
	v_fma_f32 v68, -v40, v50, 1.0
	v_fmac_f32_e32 v50, v68, v50
	v_div_scale_f32 v68, vcc, v93, v95, v93
	v_mul_f32_e32 v73, v68, v50
	v_fma_f32 v85, -v40, v73, v68
	v_fmac_f32_e32 v73, v85, v50
	v_fma_f32 v40, -v40, v73, v68
	v_div_fmas_f32 v40, v40, v50, v73
	v_div_fixup_f32 v68, v40, v95, v93
	v_div_scale_f32 v40, s[34:35], v94, v94, v92
	v_rcp_f32_e32 v50, v40
	v_and_b32_e32 v93, 0xffff0000, v53
	v_fma_f32 v73, -v40, v50, 1.0
	v_fmac_f32_e32 v50, v73, v50
	v_div_scale_f32 v73, vcc, v92, v94, v92
	v_mul_f32_e32 v85, v73, v50
	v_fma_f32 v86, -v40, v85, v73
	v_fmac_f32_e32 v85, v86, v50
	v_fma_f32 v40, -v40, v85, v73
	v_div_fmas_f32 v40, v40, v50, v85
	v_div_fixup_f32 v73, v40, v94, v92
	v_lshlrev_b32_e32 v92, 16, v53
	v_pk_fma_f32 v[58:59], v[26:27], v[92:93], v[58:59]
	v_pk_fma_f32 v[64:65], v[18:19], v[92:93], v[64:65]
	v_mul_f32_e32 v40, 0xbfb8aa3b, v58
	v_exp_f32_e32 v94, v40
	v_mul_f32_e32 v40, 0xbfb8aa3b, v59
	v_exp_f32_e32 v95, v40
	v_pk_fma_f32 v[76:77], v[10:11], v[92:93], v[76:77]
	v_pk_add_f32 v[94:95], v[94:95], 1.0 op_sel_hi:[1,0]
	s_nop 0
	v_div_scale_f32 v40, s[34:35], v95, v95, v59
	v_rcp_f32_e32 v50, v40
	s_nop 0
	v_fma_f32 v53, -v40, v50, 1.0
	v_fmac_f32_e32 v50, v53, v50
	v_div_scale_f32 v53, vcc, v59, v95, v59
	v_mul_f32_e32 v85, v53, v50
	v_fma_f32 v86, -v40, v85, v53
	v_fmac_f32_e32 v85, v86, v50
	v_fma_f32 v40, -v40, v85, v53
	v_div_fmas_f32 v40, v40, v50, v85
	v_div_scale_f32 v50, s[34:35], v94, v94, v58
	v_rcp_f32_e32 v53, v50
	v_div_fixup_f32 v40, v40, v95, v59
	v_fma_f32 v59, -v50, v53, 1.0
	v_fmac_f32_e32 v53, v59, v53
	v_div_scale_f32 v59, vcc, v58, v94, v58
	v_mul_f32_e32 v85, v59, v53
	v_fma_f32 v86, -v50, v85, v59
	v_fmac_f32_e32 v85, v86, v53
	v_fma_f32 v50, -v50, v85, v59
	v_div_fmas_f32 v50, v50, v53, v85
	v_div_fixup_f32 v50, v50, v94, v58
	v_lshlrev_b32_e32 v58, 16, v49
	v_and_b32_e32 v59, 0xffff0000, v49
	v_pk_fma_f32 v[64:65], v[26:27], v[58:59], v[64:65]
	v_cvt_pk_bf16_f32 v53, v50, v40
	v_mul_f32_e32 v40, 0xbfb8aa3b, v64
	v_exp_f32_e32 v94, v40
	v_mul_f32_e32 v40, 0xbfb8aa3b, v65
	v_exp_f32_e32 v95, v40
	v_pk_fma_f32 v[76:77], v[18:19], v[58:59], v[76:77]
	v_pk_add_f32 v[94:95], v[94:95], 1.0 op_sel_hi:[1,0]
	s_nop 0
	v_div_scale_f32 v40, s[34:35], v95, v95, v65
	v_rcp_f32_e32 v49, v40
	s_nop 0
	v_fma_f32 v50, -v40, v49, 1.0
	v_fmac_f32_e32 v49, v50, v49
	v_div_scale_f32 v50, vcc, v65, v95, v65
	v_mul_f32_e32 v85, v50, v49
	v_fma_f32 v86, -v40, v85, v50
	v_fmac_f32_e32 v85, v86, v49
	v_fma_f32 v40, -v40, v85, v50
	v_div_fmas_f32 v40, v40, v49, v85
	v_div_scale_f32 v49, s[34:35], v94, v94, v64
	v_rcp_f32_e32 v50, v49
	v_div_fixup_f32 v40, v40, v95, v65
	v_fma_f32 v65, -v49, v50, 1.0
	v_fmac_f32_e32 v50, v65, v50
	v_div_scale_f32 v65, vcc, v64, v94, v64
	v_mul_f32_e32 v85, v65, v50
	v_fma_f32 v86, -v49, v85, v65
	v_fmac_f32_e32 v85, v86, v50
	v_fma_f32 v49, -v49, v85, v65
	v_div_fmas_f32 v49, v49, v50, v85
	v_div_fixup_f32 v49, v49, v94, v64
	v_lshlrev_b32_e32 v64, 16, v45
	v_and_b32_e32 v65, 0xffff0000, v45
	v_pk_fma_f32 v[76:77], v[26:27], v[64:65], v[76:77]
	v_cvt_pk_bf16_f32 v49, v49, v40
	v_mul_f32_e32 v40, 0xbfb8aa3b, v76
	v_exp_f32_e32 v94, v40
	v_mul_f32_e32 v40, 0xbfb8aa3b, v77
	v_exp_f32_e32 v95, v40
	s_nop 0
	v_pk_add_f32 v[94:95], v[94:95], 1.0 op_sel_hi:[1,0]
	s_nop 0
	v_div_scale_f32 v40, s[34:35], v95, v95, v77
	v_rcp_f32_e32 v45, v40
	s_nop 0
	v_fma_f32 v50, -v40, v45, 1.0
	v_fmac_f32_e32 v45, v50, v45
	v_div_scale_f32 v50, vcc, v77, v95, v77
	v_mul_f32_e32 v85, v50, v45
	v_fma_f32 v86, -v40, v85, v50
	v_fmac_f32_e32 v85, v86, v45
	v_fma_f32 v40, -v40, v85, v50
	v_div_fmas_f32 v40, v40, v45, v85
	v_div_scale_f32 v45, s[34:35], v94, v94, v76
	v_rcp_f32_e32 v50, v45
	v_div_fixup_f32 v40, v40, v95, v77
	v_fma_f32 v77, -v45, v50, 1.0
	v_fmac_f32_e32 v50, v77, v50
	v_div_scale_f32 v77, vcc, v76, v94, v76
	v_mul_f32_e32 v85, v77, v50
	v_fma_f32 v86, -v45, v85, v77
	v_fmac_f32_e32 v85, v86, v50
	v_fma_f32 v45, -v45, v85, v77
	v_div_fmas_f32 v45, v45, v50, v85
	v_div_fixup_f32 v45, v45, v94, v76
	v_cvt_pk_bf16_f32 v45, v45, v40
	v_lshlrev_b32_e32 v76, 16, v41
	v_and_b32_e32 v77, 0xffff0000, v41
	v_pk_fma_f32 v[40:41], v[6:7], v[92:93], v[38:39]
	s_nop 0
	v_pk_fma_f32 v[40:41], v[10:11], v[58:59], v[40:41]
	s_nop 0
	v_pk_fma_f32 v[40:41], v[18:19], v[64:65], v[40:41]
	s_nop 0
	v_pk_fma_f32 v[40:41], v[26:27], v[76:77], v[40:41]
	s_nop 0
	v_mul_f32_e32 v50, 0xbfb8aa3b, v40
	v_exp_f32_e32 v92, v50
	v_mul_f32_e32 v50, 0xbfb8aa3b, v41
	v_exp_f32_e32 v93, v50
	s_nop 0
	v_pk_add_f32 v[92:93], v[92:93], 1.0 op_sel_hi:[1,0]
	s_nop 0
	v_div_scale_f32 v50, s[34:35], v93, v93, v41
	v_rcp_f32_e32 v85, v50
	s_nop 0
	v_fma_f32 v86, -v50, v85, 1.0
	v_fmac_f32_e32 v85, v86, v85
	v_div_scale_f32 v86, vcc, v41, v93, v41
	v_mul_f32_e32 v94, v86, v85
	v_fma_f32 v95, -v50, v94, v86
	v_fmac_f32_e32 v94, v95, v85
	v_fma_f32 v50, -v50, v94, v86
	v_div_fmas_f32 v50, v50, v85, v94
	v_div_fixup_f32 v96, v50, v93, v41
	v_div_scale_f32 v41, s[34:35], v92, v92, v40
	v_rcp_f32_e32 v50, v41
	v_lshlrev_b32_e32 v94, 16, v54
	v_and_b32_e32 v95, 0xffff0000, v54
	v_fma_f32 v85, -v41, v50, 1.0
	v_fmac_f32_e32 v50, v85, v50
	v_div_scale_f32 v85, vcc, v40, v92, v40
	v_mul_f32_e32 v86, v85, v50
	v_fma_f32 v93, -v41, v86, v85
	v_fmac_f32_e32 v86, v93, v50
	v_fma_f32 v41, -v41, v86, v85
	v_div_fmas_f32 v41, v41, v50, v86
	v_mov_b32_e32 v85, v57
	v_div_fixup_f32 v97, v41, v92, v40
	v_pk_fma_f32 v[40:41], v[0:1], v[84:85], v[32:33]
	v_and_b32_e32 v93, 0xffff0000, v42
	v_pk_fma_f32 v[40:41], v[12:13], v[82:83], v[40:41]
	v_pk_fma_f32 v[82:83], v[0:1], v[82:83], v[32:33]
	v_pk_fma_f32 v[40:41], v[20:21], v[80:81], v[40:41]
	v_pk_fma_f32 v[82:83], v[12:13], v[80:81], v[82:83]
	v_pk_fma_f32 v[40:41], v[28:29], v[94:95], v[40:41]
	v_pk_fma_f32 v[82:83], v[20:21], v[94:95], v[82:83]
	v_mul_f32_e32 v50, 0xbfb8aa3b, v40
	v_exp_f32_e32 v84, v50
	v_mul_f32_e32 v50, 0xbfb8aa3b, v41
	v_exp_f32_e32 v85, v50
	v_pk_fma_f32 v[80:81], v[0:1], v[80:81], v[32:33]
	v_pk_add_f32 v[84:85], v[84:85], 1.0 op_sel_hi:[1,0]
	s_nop 0
	v_div_scale_f32 v50, s[34:35], v85, v85, v41
	v_rcp_f32_e32 v54, v50
	v_pk_fma_f32 v[80:81], v[12:13], v[94:95], v[80:81]
	v_fma_f32 v57, -v50, v54, 1.0
	v_fmac_f32_e32 v54, v57, v54
	v_div_scale_f32 v57, vcc, v41, v85, v41
	v_mul_f32_e32 v86, v57, v54
	v_fma_f32 v92, -v50, v86, v57
	v_fmac_f32_e32 v86, v92, v54
	v_fma_f32 v50, -v50, v86, v57
	v_div_fmas_f32 v50, v50, v54, v86
	v_div_fixup_f32 v41, v50, v85, v41
	v_div_scale_f32 v50, s[34:35], v84, v84, v40
	v_rcp_f32_e32 v54, v50
	v_lshlrev_b32_e32 v92, 16, v42
	v_fma_f32 v57, -v50, v54, 1.0
	v_fmac_f32_e32 v54, v57, v54
	v_div_scale_f32 v57, vcc, v40, v84, v40
	v_mul_f32_e32 v85, v57, v54
	v_fma_f32 v86, -v50, v85, v57
	v_fmac_f32_e32 v85, v86, v54
	v_mov_b32_e32 v86, v88
	v_pk_fma_f32 v[82:83], v[28:29], v[86:87], v[82:83]
	v_fma_f32 v50, -v50, v85, v57
	v_mul_f32_e32 v42, 0xbfb8aa3b, v83
	v_div_fmas_f32 v50, v50, v54, v85
	v_exp_f32_e32 v85, v42
	v_mul_f32_e32 v42, 0xbfb8aa3b, v82
	v_div_fixup_f32 v40, v50, v84, v40
	v_exp_f32_e32 v84, v42
	v_cvt_pk_bf16_f32 v54, v40, v41
	v_lshlrev_b32_e32 v40, 16, v46
	v_and_b32_e32 v41, 0xffff0000, v46
	v_pk_add_f32 v[84:85], v[84:85], 1.0 op_sel_hi:[1,0]
	v_pk_fma_f32 v[80:81], v[20:21], v[86:87], v[80:81]
	v_div_scale_f32 v42, s[34:35], v85, v85, v83
	v_rcp_f32_e32 v46, v42
	v_pk_fma_f32 v[80:81], v[28:29], v[40:41], v[80:81]
	v_fma_f32 v50, -v42, v46, 1.0
	v_fmac_f32_e32 v46, v50, v46
	v_div_scale_f32 v50, vcc, v83, v85, v83
	v_mul_f32_e32 v57, v50, v46
	v_fma_f32 v98, -v42, v57, v50
	v_fmac_f32_e32 v57, v98, v46
	v_fma_f32 v42, -v42, v57, v50
	v_div_fmas_f32 v42, v42, v46, v57
	v_div_scale_f32 v46, s[34:35], v84, v84, v82
	v_rcp_f32_e32 v50, v46
	v_div_fixup_f32 v42, v42, v85, v83
	v_fma_f32 v57, -v46, v50, 1.0
	v_fmac_f32_e32 v50, v57, v50
	v_div_scale_f32 v57, vcc, v82, v84, v82
	v_mul_f32_e32 v83, v57, v50
	v_fma_f32 v85, -v46, v83, v57
	v_fmac_f32_e32 v83, v85, v50
	v_fma_f32 v46, -v46, v83, v57
	v_div_fmas_f32 v46, v46, v50, v83
	v_div_fixup_f32 v46, v46, v84, v82
	v_cvt_pk_bf16_f32 v50, v46, v42
	v_mul_f32_e32 v42, 0xbfb8aa3b, v81
	v_exp_f32_e32 v83, v42
	v_mul_f32_e32 v42, 0xbfb8aa3b, v80
	v_exp_f32_e32 v82, v42
	s_nop 0
	v_pk_add_f32 v[82:83], v[82:83], 1.0 op_sel_hi:[1,0]
	s_nop 0
	v_div_scale_f32 v42, s[34:35], v83, v83, v81
	v_rcp_f32_e32 v46, v42
	s_nop 0
	v_fma_f32 v57, -v42, v46, 1.0
	v_fmac_f32_e32 v46, v57, v46
	v_div_scale_f32 v57, vcc, v81, v83, v81
	v_mul_f32_e32 v84, v57, v46
	v_fma_f32 v85, -v42, v84, v57
	v_fmac_f32_e32 v84, v85, v46
	v_fma_f32 v42, -v42, v84, v57
	v_div_fmas_f32 v42, v42, v46, v84
	v_div_scale_f32 v46, s[34:35], v82, v82, v80
	v_rcp_f32_e32 v57, v46
	v_div_fixup_f32 v42, v42, v83, v81
	v_fma_f32 v81, -v46, v57, 1.0
	v_fmac_f32_e32 v57, v81, v57
	v_div_scale_f32 v81, vcc, v80, v82, v80
	v_mul_f32_e32 v83, v81, v57
	v_fma_f32 v84, -v46, v83, v81
	v_fmac_f32_e32 v83, v84, v57
	v_fma_f32 v46, -v46, v83, v81
	v_div_fmas_f32 v46, v46, v57, v83
	v_div_fixup_f32 v46, v46, v82, v80
	v_pk_fma_f32 v[80:81], v[0:1], v[94:95], v[32:33]
	v_cvt_pk_bf16_f32 v46, v46, v42
	v_pk_fma_f32 v[80:81], v[12:13], v[86:87], v[80:81]
	s_nop 0
	v_pk_fma_f32 v[80:81], v[20:21], v[40:41], v[80:81]
	s_nop 0
	v_pk_fma_f32 v[80:81], v[28:29], v[92:93], v[80:81]
	s_nop 0
	v_mul_f32_e32 v42, 0xbfb8aa3b, v80
	v_exp_f32_e32 v82, v42
	v_mul_f32_e32 v42, 0xbfb8aa3b, v81
	v_exp_f32_e32 v83, v42
	s_nop 0
	v_pk_add_f32 v[82:83], v[82:83], 1.0 op_sel_hi:[1,0]
	s_nop 0
	v_div_scale_f32 v42, s[34:35], v83, v83, v81
	v_rcp_f32_e32 v57, v42
	s_nop 0
	v_fma_f32 v84, -v42, v57, 1.0
	v_fmac_f32_e32 v57, v84, v57
	v_div_scale_f32 v84, vcc, v81, v83, v81
	v_mul_f32_e32 v85, v84, v57
	v_fma_f32 v86, -v42, v85, v84
	v_fmac_f32_e32 v85, v86, v57
	v_fma_f32 v42, -v42, v85, v84
	v_div_fmas_f32 v42, v42, v57, v85
	v_div_scale_f32 v57, s[34:35], v82, v82, v80
	v_div_fixup_f32 v42, v42, v83, v81
	v_rcp_f32_e32 v81, v57
	s_nop 0
	v_fma_f32 v83, -v57, v81, 1.0
	v_fmac_f32_e32 v81, v83, v81
	v_div_scale_f32 v83, vcc, v80, v82, v80
	v_mul_f32_e32 v84, v83, v81
	v_fma_f32 v85, -v57, v84, v83
	v_fmac_f32_e32 v84, v85, v81
	v_fma_f32 v57, -v57, v84, v83
	v_div_fmas_f32 v57, v57, v81, v84
	v_div_fixup_f32 v57, v57, v82, v80
	v_lshlrev_b32_e32 v80, 16, v55
	v_and_b32_e32 v81, 0xffff0000, v55
	v_pk_fma_f32 v[62:63], v[30:31], v[80:81], v[62:63]
	s_nop 0
	v_mul_f32_e32 v55, 0xbfb8aa3b, v62
	v_exp_f32_e32 v82, v55
	v_mul_f32_e32 v55, 0xbfb8aa3b, v63
	v_exp_f32_e32 v83, v55
	s_nop 0
	v_pk_add_f32 v[82:83], v[82:83], 1.0 op_sel_hi:[1,0]
	s_nop 0
	v_div_scale_f32 v55, s[34:35], v83, v83, v63
	v_rcp_f32_e32 v84, v55
	s_nop 0
	v_fma_f32 v85, -v55, v84, 1.0
	v_fmac_f32_e32 v84, v85, v84
	v_div_scale_f32 v85, vcc, v63, v83, v63
	v_mul_f32_e32 v86, v85, v84
	v_fma_f32 v94, -v55, v86, v85
	v_fmac_f32_e32 v86, v94, v84
	v_fma_f32 v55, -v55, v86, v85
	v_div_fmas_f32 v55, v55, v84, v86
	v_div_fixup_f32 v55, v55, v83, v63
	v_div_scale_f32 v63, s[34:35], v82, v82, v62
	v_rcp_f32_e32 v83, v63
	s_nop 0
	v_fma_f32 v84, -v63, v83, 1.0
	v_fmac_f32_e32 v83, v84, v83
	v_div_scale_f32 v84, vcc, v62, v82, v62
	v_mul_f32_e32 v85, v84, v83
	v_fma_f32 v86, -v63, v85, v84
	v_fmac_f32_e32 v85, v86, v83
	v_fma_f32 v63, -v63, v85, v84
	v_div_fmas_f32 v63, v63, v83, v85
	v_div_fixup_f32 v62, v63, v82, v62
	v_cvt_pk_bf16_f32 v55, v62, v55
	v_add_co_u32_e32 v62, vcc, s15, v90
	v_mov_b64_e32 v[84:85], v[88:89]
	s_nop 0
	v_addc_co_u32_e32 v63, vcc, 0, v91, vcc
	global_store_dwordx4 v[62:63], v[52:55], off
	v_lshlrev_b32_e32 v62, 16, v51
	v_and_b32_e32 v63, 0xffff0000, v51
	v_pk_fma_f32 v[52:53], v[2:3], v[70:71], v[34:35]
	s_nop 0
	v_pk_fma_f32 v[52:53], v[14:15], v[74:75], v[52:53]
	s_nop 0
	v_pk_fma_f32 v[52:53], v[22:23], v[80:81], v[52:53]
	s_nop 0
	v_pk_fma_f32 v[52:53], v[30:31], v[62:63], v[52:53]
	s_nop 0
	v_mul_f32_e32 v51, 0xbfb8aa3b, v52
	v_exp_f32_e32 v54, v51
	v_mul_f32_e32 v51, 0xbfb8aa3b, v53
	v_exp_f32_e32 v55, v51
	s_nop 0
	v_pk_add_f32 v[54:55], v[54:55], 1.0 op_sel_hi:[1,0]
	s_nop 0
	v_div_scale_f32 v51, s[34:35], v55, v55, v53
	v_rcp_f32_e32 v70, v51
	s_nop 0
	v_fma_f32 v71, -v51, v70, 1.0
	v_fmac_f32_e32 v70, v71, v70
	v_div_scale_f32 v71, vcc, v53, v55, v53
	v_mul_f32_e32 v82, v71, v70
	v_fma_f32 v83, -v51, v82, v71
	v_fmac_f32_e32 v82, v83, v70
	v_fma_f32 v51, -v51, v82, v71
	v_div_fmas_f32 v51, v51, v70, v82
	v_div_fixup_f32 v51, v51, v55, v53
	v_div_scale_f32 v53, s[34:35], v54, v54, v52
	v_rcp_f32_e32 v55, v53
	s_nop 0
	v_fma_f32 v70, -v53, v55, 1.0
	v_fmac_f32_e32 v55, v70, v55
	v_div_scale_f32 v70, vcc, v52, v54, v52
	v_mul_f32_e32 v71, v70, v55
	v_fma_f32 v82, -v53, v71, v70
	v_fmac_f32_e32 v71, v82, v55
	v_fma_f32 v53, -v53, v71, v70
	v_div_fmas_f32 v53, v53, v55, v71
	v_div_fixup_f32 v52, v53, v54, v52
	v_cvt_pk_bf16_f32 v51, v52, v51
	v_pk_fma_f32 v[52:53], v[2:3], v[74:75], v[34:35]
	v_lshlrev_b32_e32 v70, 16, v47
	v_pk_fma_f32 v[52:53], v[14:15], v[80:81], v[52:53]
	v_and_b32_e32 v71, 0xffff0000, v47
	v_pk_fma_f32 v[52:53], v[22:23], v[62:63], v[52:53]
	s_nop 0
	v_pk_fma_f32 v[52:53], v[30:31], v[70:71], v[52:53]
	s_nop 0
	v_mul_f32_e32 v47, 0xbfb8aa3b, v52
	v_exp_f32_e32 v54, v47
	v_mul_f32_e32 v47, 0xbfb8aa3b, v53
	v_exp_f32_e32 v55, v47
	s_nop 0
	v_pk_add_f32 v[54:55], v[54:55], 1.0 op_sel_hi:[1,0]
	s_nop 0
	v_div_scale_f32 v47, s[34:35], v55, v55, v53
	v_rcp_f32_e32 v74, v47
	s_nop 0
	v_fma_f32 v75, -v47, v74, 1.0
	v_fmac_f32_e32 v74, v75, v74
	v_div_scale_f32 v75, vcc, v53, v55, v53
	v_mul_f32_e32 v82, v75, v74
	v_fma_f32 v83, -v47, v82, v75
	v_fmac_f32_e32 v82, v83, v74
	v_fma_f32 v47, -v47, v82, v75
	v_div_fmas_f32 v47, v47, v74, v82
	v_div_fixup_f32 v47, v47, v55, v53
	v_div_scale_f32 v53, s[34:35], v54, v54, v52
	v_rcp_f32_e32 v55, v53
	s_nop 0
	v_fma_f32 v74, -v53, v55, 1.0
	v_fmac_f32_e32 v55, v74, v55
	v_div_scale_f32 v74, vcc, v52, v54, v52
	v_mul_f32_e32 v75, v74, v55
	v_fma_f32 v82, -v53, v75, v74
	v_fmac_f32_e32 v75, v82, v55
	v_fma_f32 v53, -v53, v75, v74
	v_div_fmas_f32 v53, v53, v55, v75
	v_div_fixup_f32 v52, v53, v54, v52
	v_cvt_pk_bf16_f32 v47, v52, v47
	v_add_co_u32_e32 v52, vcc, s24, v90
	v_lshlrev_b32_e32 v74, 16, v43
	s_nop 0
	v_addc_co_u32_e32 v53, vcc, 0, v91, vcc
	global_store_dwordx4 v[52:53], v[48:51], off offset:2048
	v_and_b32_e32 v75, 0xffff0000, v43
	v_mov_b64_e32 v[82:83], v[40:41]
	v_add_co_u32_e32 v48, vcc, s25, v90
	s_nop 1
	v_addc_co_u32_e32 v49, vcc, 0, v91, vcc
	global_store_dwordx4 v[48:49], v[44:47], off
	s_nop 1
	v_pk_fma_f32 v[44:45], v[2:3], v[80:81], v[34:35]
	v_mov_b64_e32 v[80:81], v[92:93]
	v_pk_fma_f32 v[44:45], v[14:15], v[62:63], v[44:45]
	s_nop 0
	v_pk_fma_f32 v[44:45], v[22:23], v[70:71], v[44:45]
	s_nop 0
	v_pk_fma_f32 v[44:45], v[30:31], v[74:75], v[44:45]
	s_nop 0
	v_mul_f32_e32 v43, 0xbfb8aa3b, v44
	v_exp_f32_e32 v46, v43
	v_mul_f32_e32 v43, 0xbfb8aa3b, v45
	v_exp_f32_e32 v47, v43
	s_nop 0
	v_pk_add_f32 v[46:47], v[46:47], 1.0 op_sel_hi:[1,0]
	s_nop 0
	v_div_scale_f32 v43, s[34:35], v47, v47, v45
	v_rcp_f32_e32 v48, v43
	s_nop 0
	v_fma_f32 v49, -v43, v48, 1.0
	v_fmac_f32_e32 v48, v49, v48
	v_div_scale_f32 v49, vcc, v45, v47, v45
	v_mul_f32_e32 v50, v49, v48
	v_fma_f32 v51, -v43, v50, v49
	v_fmac_f32_e32 v50, v51, v48
	v_fma_f32 v43, -v43, v50, v49
	v_div_fmas_f32 v43, v43, v48, v50
	v_div_fixup_f32 v43, v43, v47, v45
	v_div_scale_f32 v45, s[34:35], v46, v46, v44
	v_rcp_f32_e32 v47, v45
	s_nop 0
	v_fma_f32 v48, -v45, v47, 1.0
	v_fmac_f32_e32 v47, v48, v47
	v_div_scale_f32 v48, vcc, v44, v46, v44
	v_mul_f32_e32 v49, v48, v47
	v_fma_f32 v50, -v45, v49, v48
	v_fmac_f32_e32 v49, v50, v47
	v_fma_f32 v45, -v45, v49, v48
	v_div_fmas_f32 v45, v45, v47, v49
	v_div_fixup_f32 v47, v45, v46, v44
	v_cvt_pk_bf16_f32 v46, v57, v42
	v_add_co_u32_e32 v42, vcc, s28, v90
	v_cvt_pk_bf16_f32 v44, v73, v68
	v_cvt_pk_bf16_f32 v45, v97, v96
	v_cvt_pk_bf16_f32 v47, v47, v43
	v_addc_co_u32_e32 v43, vcc, 0, v91, vcc
	v_mov_b32_e32 v57, v87
	global_store_dwordx4 v[42:43], v[44:47], off offset:2048
	s_cbranch_scc0 .LBB0_329
	s_cmpk_lg_i32 s82, 0x800
	s_cbranch_scc1 .Lconv_orig_inc
	s_cmpk_gt_i32 s29, 0x7ff
	s_cbranch_scc1 .LBB0_331
	s_cmp_gt_u32 s33, 3
	s_cbranch_scc1 .LBB0_331
	s_lshl_b32 s29, s76, 2
	s_add_i32 s29, s29, s33
	s_addk_i32 s29, 0x800
	s_branch .LBB0_325
.Lconv_orig_inc:
	s_add_i32 s29, s29, s82
	s_cmpk_gt_i32 s29, 0xbff
	s_cbranch_scc0 .LBB0_325
